# EpiPle rolling half-group pipeline; up_rescale double-buffered gate loads
# baseline (speedup 1.0000x reference)
.LBB0_758:
	s_andn2_b64 vcc, exec, s[8:9]
	s_cbranch_vccnz .LBB0_760
	s_load_dwordx2 s[8:9], s[0:1], 0x150
	s_cmp_eq_u32 s46, 16
	s_cselect_b32 s30, 0, 0x1000
	s_waitcnt lgkmcnt(0)
	s_add_u32 s8, s8, s30
	s_addc_u32 s9, s9, 0
	s_add_u32 s8, s8, 0x1a640000
	s_addc_u32 s9, s9, 0
	s_lshl_b32 s38, s70, 1
	v_add_u32_e32 v167, s2, v171
	v_mov_b64_e32 v[164:165], s[8:9]
	v_mad_i64_i32 v[164:165], s[8:9], v167, s37, v[164:165]
	v_lshl_add_u64 v[164:165], s[24:25], 1, v[164:165]
	v_lshlrev_b32_e32 v166, 2, v185
	v_lshl_add_u64 v[164:165], v[164:165], 0, s[38:39]
	v_ashrrev_i32_e32 v167, 31, v166
	v_lshl_add_u64 v[164:165], v[166:167], 1, v[164:165]
	v_mov_b64_e32 v[166:167], v[164:165]
	v_add_co_u32_e32 v224, vcc, s3, v166
	s_nop 1
	v_addc_co_u32_e32 v225, vcc, 0, v167, vcc
	global_load_dwordx2 v[132:133], v[166:167], off
	global_load_dwordx2 v[134:135], v[166:167], off offset:32
	global_load_dwordx2 v[136:137], v[166:167], off offset:256
	global_load_dwordx2 v[138:139], v[166:167], off offset:288
	global_load_dwordx2 v[148:149], v[224:225], off
	global_load_dwordx2 v[150:151], v[224:225], off offset:32
	global_load_dwordx2 v[152:153], v[224:225], off offset:256
	global_load_dwordx2 v[154:155], v[224:225], off offset:288
	v_add_co_u32_e32 v166, vcc, 0x30000, v166
	s_nop 1
	v_addc_co_u32_e32 v167, vcc, 0, v167, vcc
	v_add_co_u32_e32 v224, vcc, 0x30000, v224
	s_nop 1
	v_addc_co_u32_e32 v225, vcc, 0, v225, vcc
	global_load_dwordx2 v[140:141], v[166:167], off
	global_load_dwordx2 v[142:143], v[166:167], off offset:32
	global_load_dwordx2 v[144:145], v[166:167], off offset:256
	global_load_dwordx2 v[146:147], v[166:167], off offset:288
	global_load_dwordx2 v[156:157], v[224:225], off
	global_load_dwordx2 v[158:159], v[224:225], off offset:32
	global_load_dwordx2 v[160:161], v[224:225], off offset:256
	global_load_dwordx2 v[162:163], v[224:225], off offset:288
	v_add_co_u32_e32 v166, vcc, 0x60000, v164
	s_nop 1
	v_addc_co_u32_e32 v167, vcc, 0, v165, vcc
	v_add_co_u32_e32 v224, vcc, s3, v166
	s_nop 1
	v_addc_co_u32_e32 v225, vcc, 0, v167, vcc
	global_load_dwordx2 v[204:205], v[166:167], off
	global_load_dwordx2 v[206:207], v[166:167], off offset:32
	global_load_dwordx2 v[208:209], v[166:167], off offset:256
	global_load_dwordx2 v[210:211], v[166:167], off offset:288
	global_load_dwordx2 v[220:221], v[224:225], off
	global_load_dwordx2 v[222:223], v[224:225], off offset:32
	global_load_dwordx2 v[232:233], v[224:225], off offset:256
	global_load_dwordx2 v[234:235], v[224:225], off offset:288
	v_add_co_u32_e32 v166, vcc, 0x30000, v166
	s_nop 1
	v_addc_co_u32_e32 v167, vcc, 0, v167, vcc
	v_add_co_u32_e32 v224, vcc, 0x30000, v224
	s_nop 1
	v_addc_co_u32_e32 v225, vcc, 0, v225, vcc
	global_load_dwordx2 v[212:213], v[166:167], off
	global_load_dwordx2 v[214:215], v[166:167], off offset:32
	global_load_dwordx2 v[216:217], v[166:167], off offset:256
	global_load_dwordx2 v[218:219], v[166:167], off offset:288
	global_load_dwordx2 v[240:241], v[224:225], off
	global_load_dwordx2 v[242:243], v[224:225], off offset:32
	global_load_dwordx2 v[244:245], v[224:225], off offset:256
	global_load_dwordx2 v[246:247], v[224:225], off offset:288
	s_waitcnt vmcnt(16)
	v_lshlrev_b32_e32 v166, 16, v148
	v_and_b32_e32 v167, 0xffff0000, v148
	v_lshlrev_b32_e32 v252, 16, v149
	v_and_b32_e32 v253, 0xffff0000, v149
	v_rcp_f32_e32 v166, v166
	v_rcp_f32_e32 v167, v167
	v_rcp_f32_e32 v252, v252
	v_rcp_f32_e32 v253, v253
	v_lshlrev_b32_e32 v248, 16, v132
	v_and_b32_e32 v249, 0xffff0000, v132
	v_lshlrev_b32_e32 v250, 16, v133
	v_and_b32_e32 v251, 0xffff0000, v133
	v_pk_mul_f32 v[248:249], v[248:249], v[166:167]
	v_pk_mul_f32 v[250:251], v[250:251], v[252:253]
	v_pk_mul_f32 v[124:125], v[124:125], v[248:249]
	v_pk_mul_f32 v[126:127], v[126:127], v[250:251]
	v_lshlrev_b32_e32 v166, 16, v150
	v_and_b32_e32 v167, 0xffff0000, v150
	v_lshlrev_b32_e32 v252, 16, v151
	v_and_b32_e32 v253, 0xffff0000, v151
	v_rcp_f32_e32 v166, v166
	v_rcp_f32_e32 v167, v167
	v_rcp_f32_e32 v252, v252
	v_rcp_f32_e32 v253, v253
	v_lshlrev_b32_e32 v248, 16, v134
	v_and_b32_e32 v249, 0xffff0000, v134
	v_lshlrev_b32_e32 v250, 16, v135
	v_and_b32_e32 v251, 0xffff0000, v135
	v_pk_mul_f32 v[248:249], v[248:249], v[166:167]
	v_pk_mul_f32 v[250:251], v[250:251], v[252:253]
	v_pk_mul_f32 v[120:121], v[120:121], v[248:249]
	v_pk_mul_f32 v[122:123], v[122:123], v[250:251]
	v_lshlrev_b32_e32 v166, 16, v152
	v_and_b32_e32 v167, 0xffff0000, v152
	v_lshlrev_b32_e32 v252, 16, v153
	v_and_b32_e32 v253, 0xffff0000, v153
	v_rcp_f32_e32 v166, v166
	v_rcp_f32_e32 v167, v167
	v_rcp_f32_e32 v252, v252
	v_rcp_f32_e32 v253, v253
	v_lshlrev_b32_e32 v248, 16, v136
	v_and_b32_e32 v249, 0xffff0000, v136
	v_lshlrev_b32_e32 v250, 16, v137
	v_and_b32_e32 v251, 0xffff0000, v137
	v_pk_mul_f32 v[248:249], v[248:249], v[166:167]
	v_pk_mul_f32 v[250:251], v[250:251], v[252:253]
	v_pk_mul_f32 v[116:117], v[116:117], v[248:249]
	v_pk_mul_f32 v[118:119], v[118:119], v[250:251]
	v_lshlrev_b32_e32 v166, 16, v154
	v_and_b32_e32 v167, 0xffff0000, v154
	v_lshlrev_b32_e32 v252, 16, v155
	v_and_b32_e32 v253, 0xffff0000, v155
	v_rcp_f32_e32 v166, v166
	v_rcp_f32_e32 v167, v167
	v_rcp_f32_e32 v252, v252
	v_rcp_f32_e32 v253, v253
	v_lshlrev_b32_e32 v248, 16, v138
	v_and_b32_e32 v249, 0xffff0000, v138
	v_lshlrev_b32_e32 v250, 16, v139
	v_and_b32_e32 v251, 0xffff0000, v139
	v_pk_mul_f32 v[248:249], v[248:249], v[166:167]
	v_pk_mul_f32 v[250:251], v[250:251], v[252:253]
	v_pk_mul_f32 v[112:113], v[112:113], v[248:249]
	v_pk_mul_f32 v[114:115], v[114:115], v[250:251]
	v_lshlrev_b32_e32 v166, 16, v156
	v_and_b32_e32 v167, 0xffff0000, v156
	v_lshlrev_b32_e32 v252, 16, v157
	v_and_b32_e32 v253, 0xffff0000, v157
	v_rcp_f32_e32 v166, v166
	v_rcp_f32_e32 v167, v167
	v_rcp_f32_e32 v252, v252
	v_rcp_f32_e32 v253, v253
	v_lshlrev_b32_e32 v248, 16, v140
	v_and_b32_e32 v249, 0xffff0000, v140
	v_lshlrev_b32_e32 v250, 16, v141
	v_and_b32_e32 v251, 0xffff0000, v141
	v_pk_mul_f32 v[248:249], v[248:249], v[166:167]
	v_pk_mul_f32 v[250:251], v[250:251], v[252:253]
	v_pk_mul_f32 v[108:109], v[108:109], v[248:249]
	v_pk_mul_f32 v[110:111], v[110:111], v[250:251]
	v_lshlrev_b32_e32 v166, 16, v158
	v_and_b32_e32 v167, 0xffff0000, v158
	v_lshlrev_b32_e32 v252, 16, v159
	v_and_b32_e32 v253, 0xffff0000, v159
	v_rcp_f32_e32 v166, v166
	v_rcp_f32_e32 v167, v167
	v_rcp_f32_e32 v252, v252
	v_rcp_f32_e32 v253, v253
	v_lshlrev_b32_e32 v248, 16, v142
	v_and_b32_e32 v249, 0xffff0000, v142
	v_lshlrev_b32_e32 v250, 16, v143
	v_and_b32_e32 v251, 0xffff0000, v143
	v_pk_mul_f32 v[248:249], v[248:249], v[166:167]
	v_pk_mul_f32 v[250:251], v[250:251], v[252:253]
	v_pk_mul_f32 v[104:105], v[104:105], v[248:249]
	v_pk_mul_f32 v[106:107], v[106:107], v[250:251]
	v_lshlrev_b32_e32 v166, 16, v160
	v_and_b32_e32 v167, 0xffff0000, v160
	v_lshlrev_b32_e32 v252, 16, v161
	v_and_b32_e32 v253, 0xffff0000, v161
	v_rcp_f32_e32 v166, v166
	v_rcp_f32_e32 v167, v167
	v_rcp_f32_e32 v252, v252
	v_rcp_f32_e32 v253, v253
	v_lshlrev_b32_e32 v248, 16, v144
	v_and_b32_e32 v249, 0xffff0000, v144
	v_lshlrev_b32_e32 v250, 16, v145
	v_and_b32_e32 v251, 0xffff0000, v145
	v_pk_mul_f32 v[248:249], v[248:249], v[166:167]
	v_pk_mul_f32 v[250:251], v[250:251], v[252:253]
	v_pk_mul_f32 v[100:101], v[100:101], v[248:249]
	v_pk_mul_f32 v[102:103], v[102:103], v[250:251]
	v_lshlrev_b32_e32 v166, 16, v162
	v_and_b32_e32 v167, 0xffff0000, v162
	v_lshlrev_b32_e32 v252, 16, v163
	v_and_b32_e32 v253, 0xffff0000, v163
	v_rcp_f32_e32 v166, v166
	v_rcp_f32_e32 v167, v167
	v_rcp_f32_e32 v252, v252
	v_rcp_f32_e32 v253, v253
	v_lshlrev_b32_e32 v248, 16, v146
	v_and_b32_e32 v249, 0xffff0000, v146
	v_lshlrev_b32_e32 v250, 16, v147
	v_and_b32_e32 v251, 0xffff0000, v147
	v_pk_mul_f32 v[248:249], v[248:249], v[166:167]
	v_pk_mul_f32 v[250:251], v[250:251], v[252:253]
	v_pk_mul_f32 v[96:97], v[96:97], v[248:249]
	v_pk_mul_f32 v[98:99], v[98:99], v[250:251]
	v_add_co_u32_e32 v166, vcc, 0x180000, v164
	s_nop 1
	v_addc_co_u32_e32 v167, vcc, 0, v165, vcc
	v_add_co_u32_e32 v224, vcc, s3, v166
	s_nop 1
	v_addc_co_u32_e32 v225, vcc, 0, v167, vcc
	global_load_dwordx2 v[132:133], v[166:167], off
	global_load_dwordx2 v[134:135], v[166:167], off offset:32
	global_load_dwordx2 v[136:137], v[166:167], off offset:256
	global_load_dwordx2 v[138:139], v[166:167], off offset:288
	global_load_dwordx2 v[148:149], v[224:225], off
	global_load_dwordx2 v[150:151], v[224:225], off offset:32
	global_load_dwordx2 v[152:153], v[224:225], off offset:256
	global_load_dwordx2 v[154:155], v[224:225], off offset:288
	v_add_co_u32_e32 v166, vcc, 0x30000, v166
	s_nop 1
	v_addc_co_u32_e32 v167, vcc, 0, v167, vcc
	v_add_co_u32_e32 v224, vcc, 0x30000, v224
	s_nop 1
	v_addc_co_u32_e32 v225, vcc, 0, v225, vcc
	global_load_dwordx2 v[140:141], v[166:167], off
	global_load_dwordx2 v[142:143], v[166:167], off offset:32
	global_load_dwordx2 v[144:145], v[166:167], off offset:256
	global_load_dwordx2 v[146:147], v[166:167], off offset:288
	global_load_dwordx2 v[156:157], v[224:225], off
	global_load_dwordx2 v[158:159], v[224:225], off offset:32
	global_load_dwordx2 v[160:161], v[224:225], off offset:256
	global_load_dwordx2 v[162:163], v[224:225], off offset:288
	s_waitcnt vmcnt(16)
	v_lshlrev_b32_e32 v166, 16, v220
	v_and_b32_e32 v167, 0xffff0000, v220
	v_lshlrev_b32_e32 v252, 16, v221
	v_and_b32_e32 v253, 0xffff0000, v221
	v_rcp_f32_e32 v166, v166
	v_rcp_f32_e32 v167, v167
	v_rcp_f32_e32 v252, v252
	v_rcp_f32_e32 v253, v253
	v_lshlrev_b32_e32 v248, 16, v204
	v_and_b32_e32 v249, 0xffff0000, v204
	v_lshlrev_b32_e32 v250, 16, v205
	v_and_b32_e32 v251, 0xffff0000, v205
	v_pk_mul_f32 v[248:249], v[248:249], v[166:167]
	v_pk_mul_f32 v[250:251], v[250:251], v[252:253]
	v_pk_mul_f32 v[92:93], v[92:93], v[248:249]
	v_pk_mul_f32 v[94:95], v[94:95], v[250:251]
	v_lshlrev_b32_e32 v166, 16, v222
	v_and_b32_e32 v167, 0xffff0000, v222
	v_lshlrev_b32_e32 v252, 16, v223
	v_and_b32_e32 v253, 0xffff0000, v223
	v_rcp_f32_e32 v166, v166
	v_rcp_f32_e32 v167, v167
	v_rcp_f32_e32 v252, v252
	v_rcp_f32_e32 v253, v253
	v_lshlrev_b32_e32 v248, 16, v206
	v_and_b32_e32 v249, 0xffff0000, v206
	v_lshlrev_b32_e32 v250, 16, v207
	v_and_b32_e32 v251, 0xffff0000, v207
	v_pk_mul_f32 v[248:249], v[248:249], v[166:167]
	v_pk_mul_f32 v[250:251], v[250:251], v[252:253]
	v_pk_mul_f32 v[88:89], v[88:89], v[248:249]
	v_pk_mul_f32 v[90:91], v[90:91], v[250:251]
	v_lshlrev_b32_e32 v166, 16, v232
	v_and_b32_e32 v167, 0xffff0000, v232
	v_lshlrev_b32_e32 v252, 16, v233
	v_and_b32_e32 v253, 0xffff0000, v233
	v_rcp_f32_e32 v166, v166
	v_rcp_f32_e32 v167, v167
	v_rcp_f32_e32 v252, v252
	v_rcp_f32_e32 v253, v253
	v_lshlrev_b32_e32 v248, 16, v208
	v_and_b32_e32 v249, 0xffff0000, v208
	v_lshlrev_b32_e32 v250, 16, v209
	v_and_b32_e32 v251, 0xffff0000, v209
	v_pk_mul_f32 v[248:249], v[248:249], v[166:167]
	v_pk_mul_f32 v[250:251], v[250:251], v[252:253]
	v_pk_mul_f32 v[84:85], v[84:85], v[248:249]
	v_pk_mul_f32 v[86:87], v[86:87], v[250:251]
	v_lshlrev_b32_e32 v166, 16, v234
	v_and_b32_e32 v167, 0xffff0000, v234
	v_lshlrev_b32_e32 v252, 16, v235
	v_and_b32_e32 v253, 0xffff0000, v235
	v_rcp_f32_e32 v166, v166
	v_rcp_f32_e32 v167, v167
	v_rcp_f32_e32 v252, v252
	v_rcp_f32_e32 v253, v253
	v_lshlrev_b32_e32 v248, 16, v210
	v_and_b32_e32 v249, 0xffff0000, v210
	v_lshlrev_b32_e32 v250, 16, v211
	v_and_b32_e32 v251, 0xffff0000, v211
	v_pk_mul_f32 v[248:249], v[248:249], v[166:167]
	v_pk_mul_f32 v[250:251], v[250:251], v[252:253]
	v_pk_mul_f32 v[80:81], v[80:81], v[248:249]
	v_pk_mul_f32 v[82:83], v[82:83], v[250:251]
	v_lshlrev_b32_e32 v166, 16, v240
	v_and_b32_e32 v167, 0xffff0000, v240
	v_lshlrev_b32_e32 v252, 16, v241
	v_and_b32_e32 v253, 0xffff0000, v241
	v_rcp_f32_e32 v166, v166
	v_rcp_f32_e32 v167, v167
	v_rcp_f32_e32 v252, v252
	v_rcp_f32_e32 v253, v253
	v_lshlrev_b32_e32 v248, 16, v212
	v_and_b32_e32 v249, 0xffff0000, v212
	v_lshlrev_b32_e32 v250, 16, v213
	v_and_b32_e32 v251, 0xffff0000, v213
	v_pk_mul_f32 v[248:249], v[248:249], v[166:167]
	v_pk_mul_f32 v[250:251], v[250:251], v[252:253]
	v_pk_mul_f32 v[76:77], v[76:77], v[248:249]
	v_pk_mul_f32 v[78:79], v[78:79], v[250:251]
	v_lshlrev_b32_e32 v166, 16, v242
	v_and_b32_e32 v167, 0xffff0000, v242
	v_lshlrev_b32_e32 v252, 16, v243
	v_and_b32_e32 v253, 0xffff0000, v243
	v_rcp_f32_e32 v166, v166
	v_rcp_f32_e32 v167, v167
	v_rcp_f32_e32 v252, v252
	v_rcp_f32_e32 v253, v253
	v_lshlrev_b32_e32 v248, 16, v214
	v_and_b32_e32 v249, 0xffff0000, v214
	v_lshlrev_b32_e32 v250, 16, v215
	v_and_b32_e32 v251, 0xffff0000, v215
	v_pk_mul_f32 v[248:249], v[248:249], v[166:167]
	v_pk_mul_f32 v[250:251], v[250:251], v[252:253]
	v_pk_mul_f32 v[72:73], v[72:73], v[248:249]
	v_pk_mul_f32 v[74:75], v[74:75], v[250:251]
	v_lshlrev_b32_e32 v166, 16, v244
	v_and_b32_e32 v167, 0xffff0000, v244
	v_lshlrev_b32_e32 v252, 16, v245
	v_and_b32_e32 v253, 0xffff0000, v245
	v_rcp_f32_e32 v166, v166
	v_rcp_f32_e32 v167, v167
	v_rcp_f32_e32 v252, v252
	v_rcp_f32_e32 v253, v253
	v_lshlrev_b32_e32 v248, 16, v216
	v_and_b32_e32 v249, 0xffff0000, v216
	v_lshlrev_b32_e32 v250, 16, v217
	v_and_b32_e32 v251, 0xffff0000, v217
	v_pk_mul_f32 v[248:249], v[248:249], v[166:167]
	v_pk_mul_f32 v[250:251], v[250:251], v[252:253]
	v_pk_mul_f32 v[68:69], v[68:69], v[248:249]
	v_pk_mul_f32 v[70:71], v[70:71], v[250:251]
	v_lshlrev_b32_e32 v166, 16, v246
	v_and_b32_e32 v167, 0xffff0000, v246
	v_lshlrev_b32_e32 v252, 16, v247
	v_and_b32_e32 v253, 0xffff0000, v247
	v_rcp_f32_e32 v166, v166
	v_rcp_f32_e32 v167, v167
	v_rcp_f32_e32 v252, v252
	v_rcp_f32_e32 v253, v253
	v_lshlrev_b32_e32 v248, 16, v218
	v_and_b32_e32 v249, 0xffff0000, v218
	v_lshlrev_b32_e32 v250, 16, v219
	v_and_b32_e32 v251, 0xffff0000, v219
	v_pk_mul_f32 v[248:249], v[248:249], v[166:167]
	v_pk_mul_f32 v[250:251], v[250:251], v[252:253]
	v_pk_mul_f32 v[64:65], v[64:65], v[248:249]
	v_pk_mul_f32 v[66:67], v[66:67], v[250:251]
	v_add_co_u32_e32 v166, vcc, 0x1e0000, v164
	s_nop 1
	v_addc_co_u32_e32 v167, vcc, 0, v165, vcc
	v_add_co_u32_e32 v224, vcc, s3, v166
	s_nop 1
	v_addc_co_u32_e32 v225, vcc, 0, v167, vcc
	global_load_dwordx2 v[204:205], v[166:167], off
	global_load_dwordx2 v[206:207], v[166:167], off offset:32
	global_load_dwordx2 v[208:209], v[166:167], off offset:256
	global_load_dwordx2 v[210:211], v[166:167], off offset:288
	global_load_dwordx2 v[220:221], v[224:225], off
	global_load_dwordx2 v[222:223], v[224:225], off offset:32
	global_load_dwordx2 v[232:233], v[224:225], off offset:256
	global_load_dwordx2 v[234:235], v[224:225], off offset:288
	v_add_co_u32_e32 v166, vcc, 0x30000, v166
	s_nop 1
	v_addc_co_u32_e32 v167, vcc, 0, v167, vcc
	v_add_co_u32_e32 v224, vcc, 0x30000, v224
	s_nop 1
	v_addc_co_u32_e32 v225, vcc, 0, v225, vcc
	global_load_dwordx2 v[212:213], v[166:167], off
	global_load_dwordx2 v[214:215], v[166:167], off offset:32
	global_load_dwordx2 v[216:217], v[166:167], off offset:256
	global_load_dwordx2 v[218:219], v[166:167], off offset:288
	global_load_dwordx2 v[240:241], v[224:225], off
	global_load_dwordx2 v[242:243], v[224:225], off offset:32
	global_load_dwordx2 v[244:245], v[224:225], off offset:256
	global_load_dwordx2 v[246:247], v[224:225], off offset:288
	s_waitcnt vmcnt(16)
	v_lshlrev_b32_e32 v166, 16, v148
	v_and_b32_e32 v167, 0xffff0000, v148
	v_lshlrev_b32_e32 v252, 16, v149
	v_and_b32_e32 v253, 0xffff0000, v149
	v_rcp_f32_e32 v166, v166
	v_rcp_f32_e32 v167, v167
	v_rcp_f32_e32 v252, v252
	v_rcp_f32_e32 v253, v253
	v_lshlrev_b32_e32 v248, 16, v132
	v_and_b32_e32 v249, 0xffff0000, v132
	v_lshlrev_b32_e32 v250, 16, v133
	v_and_b32_e32 v251, 0xffff0000, v133
	v_pk_mul_f32 v[248:249], v[248:249], v[166:167]
	v_pk_mul_f32 v[250:251], v[250:251], v[252:253]
	v_pk_mul_f32 v[60:61], v[60:61], v[248:249]
	v_pk_mul_f32 v[62:63], v[62:63], v[250:251]
	v_lshlrev_b32_e32 v166, 16, v150
	v_and_b32_e32 v167, 0xffff0000, v150
	v_lshlrev_b32_e32 v252, 16, v151
	v_and_b32_e32 v253, 0xffff0000, v151
	v_rcp_f32_e32 v166, v166
	v_rcp_f32_e32 v167, v167
	v_rcp_f32_e32 v252, v252
	v_rcp_f32_e32 v253, v253
	v_lshlrev_b32_e32 v248, 16, v134
	v_and_b32_e32 v249, 0xffff0000, v134
	v_lshlrev_b32_e32 v250, 16, v135
	v_and_b32_e32 v251, 0xffff0000, v135
	v_pk_mul_f32 v[248:249], v[248:249], v[166:167]
	v_pk_mul_f32 v[250:251], v[250:251], v[252:253]
	v_pk_mul_f32 v[56:57], v[56:57], v[248:249]
	v_pk_mul_f32 v[58:59], v[58:59], v[250:251]
	v_lshlrev_b32_e32 v166, 16, v152
	v_and_b32_e32 v167, 0xffff0000, v152
	v_lshlrev_b32_e32 v252, 16, v153
	v_and_b32_e32 v253, 0xffff0000, v153
	v_rcp_f32_e32 v166, v166
	v_rcp_f32_e32 v167, v167
	v_rcp_f32_e32 v252, v252
	v_rcp_f32_e32 v253, v253
	v_lshlrev_b32_e32 v248, 16, v136
	v_and_b32_e32 v249, 0xffff0000, v136
	v_lshlrev_b32_e32 v250, 16, v137
	v_and_b32_e32 v251, 0xffff0000, v137
	v_pk_mul_f32 v[248:249], v[248:249], v[166:167]
	v_pk_mul_f32 v[250:251], v[250:251], v[252:253]
	v_pk_mul_f32 v[52:53], v[52:53], v[248:249]
	v_pk_mul_f32 v[54:55], v[54:55], v[250:251]
	v_lshlrev_b32_e32 v166, 16, v154
	v_and_b32_e32 v167, 0xffff0000, v154
	v_lshlrev_b32_e32 v252, 16, v155
	v_and_b32_e32 v253, 0xffff0000, v155
	v_rcp_f32_e32 v166, v166
	v_rcp_f32_e32 v167, v167
	v_rcp_f32_e32 v252, v252
	v_rcp_f32_e32 v253, v253
	v_lshlrev_b32_e32 v248, 16, v138
	v_and_b32_e32 v249, 0xffff0000, v138
	v_lshlrev_b32_e32 v250, 16, v139
	v_and_b32_e32 v251, 0xffff0000, v139
	v_pk_mul_f32 v[248:249], v[248:249], v[166:167]
	v_pk_mul_f32 v[250:251], v[250:251], v[252:253]
	v_pk_mul_f32 v[48:49], v[48:49], v[248:249]
	v_pk_mul_f32 v[50:51], v[50:51], v[250:251]
	v_lshlrev_b32_e32 v166, 16, v156
	v_and_b32_e32 v167, 0xffff0000, v156
	v_lshlrev_b32_e32 v252, 16, v157
	v_and_b32_e32 v253, 0xffff0000, v157
	v_rcp_f32_e32 v166, v166
	v_rcp_f32_e32 v167, v167
	v_rcp_f32_e32 v252, v252
	v_rcp_f32_e32 v253, v253
	v_lshlrev_b32_e32 v248, 16, v140
	v_and_b32_e32 v249, 0xffff0000, v140
	v_lshlrev_b32_e32 v250, 16, v141
	v_and_b32_e32 v251, 0xffff0000, v141
	v_pk_mul_f32 v[248:249], v[248:249], v[166:167]
	v_pk_mul_f32 v[250:251], v[250:251], v[252:253]
	v_pk_mul_f32 v[44:45], v[44:45], v[248:249]
	v_pk_mul_f32 v[46:47], v[46:47], v[250:251]
	v_lshlrev_b32_e32 v166, 16, v158
	v_and_b32_e32 v167, 0xffff0000, v158
	v_lshlrev_b32_e32 v252, 16, v159
	v_and_b32_e32 v253, 0xffff0000, v159
	v_rcp_f32_e32 v166, v166
	v_rcp_f32_e32 v167, v167
	v_rcp_f32_e32 v252, v252
	v_rcp_f32_e32 v253, v253
	v_lshlrev_b32_e32 v248, 16, v142
	v_and_b32_e32 v249, 0xffff0000, v142
	v_lshlrev_b32_e32 v250, 16, v143
	v_and_b32_e32 v251, 0xffff0000, v143
	v_pk_mul_f32 v[248:249], v[248:249], v[166:167]
	v_pk_mul_f32 v[250:251], v[250:251], v[252:253]
	v_pk_mul_f32 v[40:41], v[40:41], v[248:249]
	v_pk_mul_f32 v[42:43], v[42:43], v[250:251]
	v_lshlrev_b32_e32 v166, 16, v160
	v_and_b32_e32 v167, 0xffff0000, v160
	v_lshlrev_b32_e32 v252, 16, v161
	v_and_b32_e32 v253, 0xffff0000, v161
	v_rcp_f32_e32 v166, v166
	v_rcp_f32_e32 v167, v167
	v_rcp_f32_e32 v252, v252
	v_rcp_f32_e32 v253, v253
	v_lshlrev_b32_e32 v248, 16, v144
	v_and_b32_e32 v249, 0xffff0000, v144
	v_lshlrev_b32_e32 v250, 16, v145
	v_and_b32_e32 v251, 0xffff0000, v145
	v_pk_mul_f32 v[248:249], v[248:249], v[166:167]
	v_pk_mul_f32 v[250:251], v[250:251], v[252:253]
	v_pk_mul_f32 v[36:37], v[36:37], v[248:249]
	v_pk_mul_f32 v[38:39], v[38:39], v[250:251]
	v_lshlrev_b32_e32 v166, 16, v162
	v_and_b32_e32 v167, 0xffff0000, v162
	v_lshlrev_b32_e32 v252, 16, v163
	v_and_b32_e32 v253, 0xffff0000, v163
	v_rcp_f32_e32 v166, v166
	v_rcp_f32_e32 v167, v167
	v_rcp_f32_e32 v252, v252
	v_rcp_f32_e32 v253, v253
	v_lshlrev_b32_e32 v248, 16, v146
	v_and_b32_e32 v249, 0xffff0000, v146
	v_lshlrev_b32_e32 v250, 16, v147
	v_and_b32_e32 v251, 0xffff0000, v147
	v_pk_mul_f32 v[248:249], v[248:249], v[166:167]
	v_pk_mul_f32 v[250:251], v[250:251], v[252:253]
	v_pk_mul_f32 v[32:33], v[32:33], v[248:249]
	v_pk_mul_f32 v[34:35], v[34:35], v[250:251]
	s_waitcnt vmcnt(0)
	v_lshlrev_b32_e32 v166, 16, v220
	v_and_b32_e32 v167, 0xffff0000, v220
	v_lshlrev_b32_e32 v252, 16, v221
	v_and_b32_e32 v253, 0xffff0000, v221
	v_rcp_f32_e32 v166, v166
	v_rcp_f32_e32 v167, v167
	v_rcp_f32_e32 v252, v252
	v_rcp_f32_e32 v253, v253
	v_lshlrev_b32_e32 v248, 16, v204
	v_and_b32_e32 v249, 0xffff0000, v204
	v_lshlrev_b32_e32 v250, 16, v205
	v_and_b32_e32 v251, 0xffff0000, v205
	v_pk_mul_f32 v[248:249], v[248:249], v[166:167]
	v_pk_mul_f32 v[250:251], v[250:251], v[252:253]
	v_pk_mul_f32 v[28:29], v[28:29], v[248:249]
	v_pk_mul_f32 v[30:31], v[30:31], v[250:251]
	v_lshlrev_b32_e32 v166, 16, v222
	v_and_b32_e32 v167, 0xffff0000, v222
	v_lshlrev_b32_e32 v252, 16, v223
	v_and_b32_e32 v253, 0xffff0000, v223
	v_rcp_f32_e32 v166, v166
	v_rcp_f32_e32 v167, v167
	v_rcp_f32_e32 v252, v252
	v_rcp_f32_e32 v253, v253
	v_lshlrev_b32_e32 v248, 16, v206
	v_and_b32_e32 v249, 0xffff0000, v206
	v_lshlrev_b32_e32 v250, 16, v207
	v_and_b32_e32 v251, 0xffff0000, v207
	v_pk_mul_f32 v[248:249], v[248:249], v[166:167]
	v_pk_mul_f32 v[250:251], v[250:251], v[252:253]
	v_pk_mul_f32 v[24:25], v[24:25], v[248:249]
	v_pk_mul_f32 v[26:27], v[26:27], v[250:251]
	v_lshlrev_b32_e32 v166, 16, v232
	v_and_b32_e32 v167, 0xffff0000, v232
	v_lshlrev_b32_e32 v252, 16, v233
	v_and_b32_e32 v253, 0xffff0000, v233
	v_rcp_f32_e32 v166, v166
	v_rcp_f32_e32 v167, v167
	v_rcp_f32_e32 v252, v252
	v_rcp_f32_e32 v253, v253
	v_lshlrev_b32_e32 v248, 16, v208
	v_and_b32_e32 v249, 0xffff0000, v208
	v_lshlrev_b32_e32 v250, 16, v209
	v_and_b32_e32 v251, 0xffff0000, v209
	v_pk_mul_f32 v[248:249], v[248:249], v[166:167]
	v_pk_mul_f32 v[250:251], v[250:251], v[252:253]
	v_pk_mul_f32 v[20:21], v[20:21], v[248:249]
	v_pk_mul_f32 v[22:23], v[22:23], v[250:251]
	v_lshlrev_b32_e32 v166, 16, v234
	v_and_b32_e32 v167, 0xffff0000, v234
	v_lshlrev_b32_e32 v252, 16, v235
	v_and_b32_e32 v253, 0xffff0000, v235
	v_rcp_f32_e32 v166, v166
	v_rcp_f32_e32 v167, v167
	v_rcp_f32_e32 v252, v252
	v_rcp_f32_e32 v253, v253
	v_lshlrev_b32_e32 v248, 16, v210
	v_and_b32_e32 v249, 0xffff0000, v210
	v_lshlrev_b32_e32 v250, 16, v211
	v_and_b32_e32 v251, 0xffff0000, v211
	v_pk_mul_f32 v[248:249], v[248:249], v[166:167]
	v_pk_mul_f32 v[250:251], v[250:251], v[252:253]
	v_pk_mul_f32 v[16:17], v[16:17], v[248:249]
	v_pk_mul_f32 v[18:19], v[18:19], v[250:251]
	v_lshlrev_b32_e32 v166, 16, v240
	v_and_b32_e32 v167, 0xffff0000, v240
	v_lshlrev_b32_e32 v252, 16, v241
	v_and_b32_e32 v253, 0xffff0000, v241
	v_rcp_f32_e32 v166, v166
	v_rcp_f32_e32 v167, v167
	v_rcp_f32_e32 v252, v252
	v_rcp_f32_e32 v253, v253
	v_lshlrev_b32_e32 v248, 16, v212
	v_and_b32_e32 v249, 0xffff0000, v212
	v_lshlrev_b32_e32 v250, 16, v213
	v_and_b32_e32 v251, 0xffff0000, v213
	v_pk_mul_f32 v[248:249], v[248:249], v[166:167]
	v_pk_mul_f32 v[250:251], v[250:251], v[252:253]
	v_pk_mul_f32 v[12:13], v[12:13], v[248:249]
	v_pk_mul_f32 v[14:15], v[14:15], v[250:251]
	v_lshlrev_b32_e32 v166, 16, v242
	v_and_b32_e32 v167, 0xffff0000, v242
	v_lshlrev_b32_e32 v252, 16, v243
	v_and_b32_e32 v253, 0xffff0000, v243
	v_rcp_f32_e32 v166, v166
	v_rcp_f32_e32 v167, v167
	v_rcp_f32_e32 v252, v252
	v_rcp_f32_e32 v253, v253
	v_lshlrev_b32_e32 v248, 16, v214
	v_and_b32_e32 v249, 0xffff0000, v214
	v_lshlrev_b32_e32 v250, 16, v215
	v_and_b32_e32 v251, 0xffff0000, v215
	v_pk_mul_f32 v[248:249], v[248:249], v[166:167]
	v_pk_mul_f32 v[250:251], v[250:251], v[252:253]
	v_pk_mul_f32 v[8:9], v[8:9], v[248:249]
	v_pk_mul_f32 v[10:11], v[10:11], v[250:251]
	v_lshlrev_b32_e32 v166, 16, v244
	v_and_b32_e32 v167, 0xffff0000, v244
	v_lshlrev_b32_e32 v252, 16, v245
	v_and_b32_e32 v253, 0xffff0000, v245
	v_rcp_f32_e32 v166, v166
	v_rcp_f32_e32 v167, v167
	v_rcp_f32_e32 v252, v252
	v_rcp_f32_e32 v253, v253
	v_lshlrev_b32_e32 v248, 16, v216
	v_and_b32_e32 v249, 0xffff0000, v216
	v_lshlrev_b32_e32 v250, 16, v217
	v_and_b32_e32 v251, 0xffff0000, v217
	v_pk_mul_f32 v[248:249], v[248:249], v[166:167]
	v_pk_mul_f32 v[250:251], v[250:251], v[252:253]
	v_pk_mul_f32 v[4:5], v[4:5], v[248:249]
	v_pk_mul_f32 v[6:7], v[6:7], v[250:251]
	v_lshlrev_b32_e32 v166, 16, v246
	v_and_b32_e32 v167, 0xffff0000, v246
	v_lshlrev_b32_e32 v252, 16, v247
	v_and_b32_e32 v253, 0xffff0000, v247
	v_rcp_f32_e32 v166, v166
	v_rcp_f32_e32 v167, v167
	v_rcp_f32_e32 v252, v252
	v_rcp_f32_e32 v253, v253
	v_lshlrev_b32_e32 v248, 16, v218
	v_and_b32_e32 v249, 0xffff0000, v218
	v_lshlrev_b32_e32 v250, 16, v219
	v_and_b32_e32 v251, 0xffff0000, v219
	v_pk_mul_f32 v[248:249], v[248:249], v[166:167]
	v_pk_mul_f32 v[250:251], v[250:251], v[252:253]
	v_pk_mul_f32 v[0:1], v[0:1], v[248:249]
	v_pk_mul_f32 v[2:3], v[2:3], v[250:251]

.LBB0_801:
	s_and_b64 vcc, exec, s[44:45]
	v_add_u32_e32 v158, s54, v192
	v_add_u32_e32 v156, s54, v194
	v_add_u32_e32 v154, s54, v195
	v_add_u32_e32 v152, s54, v196
	s_cbranch_vccz .LBB0_803
	s_load_dwordx2 s[4:5], s[0:1], 0x148
	v_or_b32_e32 v190, s24, v182
	v_mov_b32_e32 v191, s25
	s_waitcnt lgkmcnt(0)
	s_add_u32 s30, s26, 0x13640000
	s_addc_u32 s31, s27, 0
	v_lshlrev_b64 v[190:191], 2, v[190:191]
	v_add_u32_e32 v250, s54, v192
	v_ashrrev_i32_e32 v251, 31, v250
	v_lshlrev_b64 v[250:251], 13, v[250:251]
	v_lshl_add_u64 v[250:251], v[250:251], 0, v[190:191]
	v_lshl_add_u64 v[164:165], v[250:251], 0, s[4:5]
	v_lshl_add_u64 v[166:167], v[250:251], 0, s[30:31]
	global_load_dwordx4 v[132:135], v[164:165], off
	global_load_dwordx4 v[136:139], v[164:165], off offset:64
	global_load_dwordx4 v[140:143], v[164:165], off offset:512
	global_load_dwordx4 v[144:147], v[164:165], off offset:576
	global_load_dwordx4 v[148:151], v[166:167], off
	global_load_dwordx4 v[152:155], v[166:167], off offset:64
	global_load_dwordx4 v[156:159], v[166:167], off offset:512
	global_load_dwordx4 v[160:163], v[166:167], off offset:576
	v_add_u32_e32 v250, s54, v194
	v_ashrrev_i32_e32 v251, 31, v250
	v_lshlrev_b64 v[250:251], 13, v[250:251]
	v_lshl_add_u64 v[250:251], v[250:251], 0, v[190:191]
	v_lshl_add_u64 v[224:225], v[250:251], 0, s[4:5]
	v_lshl_add_u64 v[248:249], v[250:251], 0, s[30:31]
	global_load_dwordx4 v[204:207], v[224:225], off
	global_load_dwordx4 v[208:211], v[224:225], off offset:64
	global_load_dwordx4 v[212:215], v[224:225], off offset:512
	global_load_dwordx4 v[216:219], v[224:225], off offset:576
	global_load_dwordx4 v[220:223], v[248:249], off
	global_load_dwordx4 v[232:235], v[248:249], off offset:64
	global_load_dwordx4 v[240:243], v[248:249], off offset:512
	global_load_dwordx4 v[244:247], v[248:249], off offset:576
	s_waitcnt vmcnt(8)
	v_mul_f32_e32 v128, 0xbfb8aa3b, v124
	v_mul_f32_e32 v129, 0xbfb8aa3b, v125
	v_mul_f32_e32 v130, 0xbfb8aa3b, v126
	v_mul_f32_e32 v131, 0xbfb8aa3b, v127
	v_exp_f32_e32 v128, v128
	v_exp_f32_e32 v129, v129
	v_exp_f32_e32 v130, v130
	v_exp_f32_e32 v131, v131
	v_add_f32_e32 v128, 1.0, v128
	v_add_f32_e32 v129, 1.0, v129
	v_add_f32_e32 v130, 1.0, v130
	v_add_f32_e32 v131, 1.0, v131
	v_rcp_f32_e32 v128, v128
	v_rcp_f32_e32 v129, v129
	v_rcp_f32_e32 v130, v130
	v_rcp_f32_e32 v131, v131
	v_pk_fma_f32 v[132:133], v[128:129], v[148:149], v[132:133]
	s_nop 0
	v_pk_fma_f32 v[134:135], v[130:131], v[150:151], v[134:135]
	global_store_dwordx4 v[164:165], v[132:135], off
	v_mul_f32_e32 v128, 0xbfb8aa3b, v120
	v_mul_f32_e32 v129, 0xbfb8aa3b, v121
	v_mul_f32_e32 v130, 0xbfb8aa3b, v122
	v_mul_f32_e32 v131, 0xbfb8aa3b, v123
	v_exp_f32_e32 v128, v128
	v_exp_f32_e32 v129, v129
	v_exp_f32_e32 v130, v130
	v_exp_f32_e32 v131, v131
	v_add_f32_e32 v128, 1.0, v128
	v_add_f32_e32 v129, 1.0, v129
	v_add_f32_e32 v130, 1.0, v130
	v_add_f32_e32 v131, 1.0, v131
	v_rcp_f32_e32 v128, v128
	v_rcp_f32_e32 v129, v129
	v_rcp_f32_e32 v130, v130
	v_rcp_f32_e32 v131, v131
	v_pk_fma_f32 v[136:137], v[128:129], v[152:153], v[136:137]
	s_nop 0
	v_pk_fma_f32 v[138:139], v[130:131], v[154:155], v[138:139]
	global_store_dwordx4 v[164:165], v[136:139], off offset:64
	v_mul_f32_e32 v128, 0xbfb8aa3b, v116
	v_mul_f32_e32 v129, 0xbfb8aa3b, v117
	v_mul_f32_e32 v130, 0xbfb8aa3b, v118
	v_mul_f32_e32 v131, 0xbfb8aa3b, v119
	v_exp_f32_e32 v128, v128
	v_exp_f32_e32 v129, v129
	v_exp_f32_e32 v130, v130
	v_exp_f32_e32 v131, v131
	v_add_f32_e32 v128, 1.0, v128
	v_add_f32_e32 v129, 1.0, v129
	v_add_f32_e32 v130, 1.0, v130
	v_add_f32_e32 v131, 1.0, v131
	v_rcp_f32_e32 v128, v128
	v_rcp_f32_e32 v129, v129
	v_rcp_f32_e32 v130, v130
	v_rcp_f32_e32 v131, v131
	v_pk_fma_f32 v[140:141], v[128:129], v[156:157], v[140:141]
	s_nop 0
	v_pk_fma_f32 v[142:143], v[130:131], v[158:159], v[142:143]
	global_store_dwordx4 v[164:165], v[140:143], off offset:512
	v_mul_f32_e32 v128, 0xbfb8aa3b, v112
	v_mul_f32_e32 v129, 0xbfb8aa3b, v113
	v_mul_f32_e32 v130, 0xbfb8aa3b, v114
	v_mul_f32_e32 v131, 0xbfb8aa3b, v115
	v_exp_f32_e32 v128, v128
	v_exp_f32_e32 v129, v129
	v_exp_f32_e32 v130, v130
	v_exp_f32_e32 v131, v131
	v_add_f32_e32 v128, 1.0, v128
	v_add_f32_e32 v129, 1.0, v129
	v_add_f32_e32 v130, 1.0, v130
	v_add_f32_e32 v131, 1.0, v131
	v_rcp_f32_e32 v128, v128
	v_rcp_f32_e32 v129, v129
	v_rcp_f32_e32 v130, v130
	v_rcp_f32_e32 v131, v131
	v_pk_fma_f32 v[144:145], v[128:129], v[160:161], v[144:145]
	s_nop 0
	v_pk_fma_f32 v[146:147], v[130:131], v[162:163], v[146:147]
	global_store_dwordx4 v[164:165], v[144:147], off offset:576
	s_nop 1
	v_add_u32_e32 v250, s54, v195
	v_ashrrev_i32_e32 v251, 31, v250
	v_lshlrev_b64 v[250:251], 13, v[250:251]
	v_lshl_add_u64 v[250:251], v[250:251], 0, v[190:191]
	v_lshl_add_u64 v[164:165], v[250:251], 0, s[4:5]
	v_lshl_add_u64 v[166:167], v[250:251], 0, s[30:31]
	global_load_dwordx4 v[132:135], v[164:165], off
	global_load_dwordx4 v[136:139], v[164:165], off offset:64
	global_load_dwordx4 v[140:143], v[164:165], off offset:512
	global_load_dwordx4 v[144:147], v[164:165], off offset:576
	global_load_dwordx4 v[148:151], v[166:167], off
	global_load_dwordx4 v[152:155], v[166:167], off offset:64
	global_load_dwordx4 v[156:159], v[166:167], off offset:512
	global_load_dwordx4 v[160:163], v[166:167], off offset:576
	s_waitcnt vmcnt(12)
	v_mul_f32_e32 v128, 0xbfb8aa3b, v108
	v_mul_f32_e32 v129, 0xbfb8aa3b, v109
	v_mul_f32_e32 v130, 0xbfb8aa3b, v110
	v_mul_f32_e32 v131, 0xbfb8aa3b, v111
	v_exp_f32_e32 v128, v128
	v_exp_f32_e32 v129, v129
	v_exp_f32_e32 v130, v130
	v_exp_f32_e32 v131, v131
	v_add_f32_e32 v128, 1.0, v128
	v_add_f32_e32 v129, 1.0, v129
	v_add_f32_e32 v130, 1.0, v130
	v_add_f32_e32 v131, 1.0, v131
	v_rcp_f32_e32 v128, v128
	v_rcp_f32_e32 v129, v129
	v_rcp_f32_e32 v130, v130
	v_rcp_f32_e32 v131, v131
	v_pk_fma_f32 v[204:205], v[128:129], v[220:221], v[204:205]
	s_nop 0
	v_pk_fma_f32 v[206:207], v[130:131], v[222:223], v[206:207]
	global_store_dwordx4 v[224:225], v[204:207], off
	v_mul_f32_e32 v128, 0xbfb8aa3b, v104
	v_mul_f32_e32 v129, 0xbfb8aa3b, v105
	v_mul_f32_e32 v130, 0xbfb8aa3b, v106
	v_mul_f32_e32 v131, 0xbfb8aa3b, v107
	v_exp_f32_e32 v128, v128
	v_exp_f32_e32 v129, v129
	v_exp_f32_e32 v130, v130
	v_exp_f32_e32 v131, v131
	v_add_f32_e32 v128, 1.0, v128
	v_add_f32_e32 v129, 1.0, v129
	v_add_f32_e32 v130, 1.0, v130
	v_add_f32_e32 v131, 1.0, v131
	v_rcp_f32_e32 v128, v128
	v_rcp_f32_e32 v129, v129
	v_rcp_f32_e32 v130, v130
	v_rcp_f32_e32 v131, v131
	v_pk_fma_f32 v[208:209], v[128:129], v[232:233], v[208:209]
	s_nop 0
	v_pk_fma_f32 v[210:211], v[130:131], v[234:235], v[210:211]
	global_store_dwordx4 v[224:225], v[208:211], off offset:64
	v_mul_f32_e32 v128, 0xbfb8aa3b, v100
	v_mul_f32_e32 v129, 0xbfb8aa3b, v101
	v_mul_f32_e32 v130, 0xbfb8aa3b, v102
	v_mul_f32_e32 v131, 0xbfb8aa3b, v103
	v_exp_f32_e32 v128, v128
	v_exp_f32_e32 v129, v129
	v_exp_f32_e32 v130, v130
	v_exp_f32_e32 v131, v131
	v_add_f32_e32 v128, 1.0, v128
	v_add_f32_e32 v129, 1.0, v129
	v_add_f32_e32 v130, 1.0, v130
	v_add_f32_e32 v131, 1.0, v131
	v_rcp_f32_e32 v128, v128
	v_rcp_f32_e32 v129, v129
	v_rcp_f32_e32 v130, v130
	v_rcp_f32_e32 v131, v131
	v_pk_fma_f32 v[212:213], v[128:129], v[240:241], v[212:213]
	s_nop 0
	v_pk_fma_f32 v[214:215], v[130:131], v[242:243], v[214:215]
	global_store_dwordx4 v[224:225], v[212:215], off offset:512
	v_mul_f32_e32 v128, 0xbfb8aa3b, v96
	v_mul_f32_e32 v129, 0xbfb8aa3b, v97
	v_mul_f32_e32 v130, 0xbfb8aa3b, v98
	v_mul_f32_e32 v131, 0xbfb8aa3b, v99
	v_exp_f32_e32 v128, v128
	v_exp_f32_e32 v129, v129
	v_exp_f32_e32 v130, v130
	v_exp_f32_e32 v131, v131
	v_add_f32_e32 v128, 1.0, v128
	v_add_f32_e32 v129, 1.0, v129
	v_add_f32_e32 v130, 1.0, v130
	v_add_f32_e32 v131, 1.0, v131
	v_rcp_f32_e32 v128, v128
	v_rcp_f32_e32 v129, v129
	v_rcp_f32_e32 v130, v130
	v_rcp_f32_e32 v131, v131
	v_pk_fma_f32 v[216:217], v[128:129], v[244:245], v[216:217]
	s_nop 0
	v_pk_fma_f32 v[218:219], v[130:131], v[246:247], v[218:219]
	global_store_dwordx4 v[224:225], v[216:219], off offset:576
	s_nop 1
	v_add_u32_e32 v250, s54, v196
	v_ashrrev_i32_e32 v251, 31, v250
	v_lshlrev_b64 v[250:251], 13, v[250:251]
	v_lshl_add_u64 v[250:251], v[250:251], 0, v[190:191]
	v_lshl_add_u64 v[224:225], v[250:251], 0, s[4:5]
	v_lshl_add_u64 v[248:249], v[250:251], 0, s[30:31]
	global_load_dwordx4 v[204:207], v[224:225], off
	global_load_dwordx4 v[208:211], v[224:225], off offset:64
	global_load_dwordx4 v[212:215], v[224:225], off offset:512
	global_load_dwordx4 v[216:219], v[224:225], off offset:576
	global_load_dwordx4 v[220:223], v[248:249], off
	global_load_dwordx4 v[232:235], v[248:249], off offset:64
	global_load_dwordx4 v[240:243], v[248:249], off offset:512
	global_load_dwordx4 v[244:247], v[248:249], off offset:576
	s_waitcnt vmcnt(12)
	v_mul_f32_e32 v128, 0xbfb8aa3b, v92
	v_mul_f32_e32 v129, 0xbfb8aa3b, v93
	v_mul_f32_e32 v130, 0xbfb8aa3b, v94
	v_mul_f32_e32 v131, 0xbfb8aa3b, v95
	v_exp_f32_e32 v128, v128
	v_exp_f32_e32 v129, v129
	v_exp_f32_e32 v130, v130
	v_exp_f32_e32 v131, v131
	v_add_f32_e32 v128, 1.0, v128
	v_add_f32_e32 v129, 1.0, v129
	v_add_f32_e32 v130, 1.0, v130
	v_add_f32_e32 v131, 1.0, v131
	v_rcp_f32_e32 v128, v128
	v_rcp_f32_e32 v129, v129
	v_rcp_f32_e32 v130, v130
	v_rcp_f32_e32 v131, v131
	v_pk_fma_f32 v[132:133], v[128:129], v[148:149], v[132:133]
	s_nop 0
	v_pk_fma_f32 v[134:135], v[130:131], v[150:151], v[134:135]
	global_store_dwordx4 v[164:165], v[132:135], off
	v_mul_f32_e32 v128, 0xbfb8aa3b, v88
	v_mul_f32_e32 v129, 0xbfb8aa3b, v89
	v_mul_f32_e32 v130, 0xbfb8aa3b, v90
	v_mul_f32_e32 v131, 0xbfb8aa3b, v91
	v_exp_f32_e32 v128, v128
	v_exp_f32_e32 v129, v129
	v_exp_f32_e32 v130, v130
	v_exp_f32_e32 v131, v131
	v_add_f32_e32 v128, 1.0, v128
	v_add_f32_e32 v129, 1.0, v129
	v_add_f32_e32 v130, 1.0, v130
	v_add_f32_e32 v131, 1.0, v131
	v_rcp_f32_e32 v128, v128
	v_rcp_f32_e32 v129, v129
	v_rcp_f32_e32 v130, v130
	v_rcp_f32_e32 v131, v131
	v_pk_fma_f32 v[136:137], v[128:129], v[152:153], v[136:137]
	s_nop 0
	v_pk_fma_f32 v[138:139], v[130:131], v[154:155], v[138:139]
	global_store_dwordx4 v[164:165], v[136:139], off offset:64
	v_mul_f32_e32 v128, 0xbfb8aa3b, v84
	v_mul_f32_e32 v129, 0xbfb8aa3b, v85
	v_mul_f32_e32 v130, 0xbfb8aa3b, v86
	v_mul_f32_e32 v131, 0xbfb8aa3b, v87
	v_exp_f32_e32 v128, v128
	v_exp_f32_e32 v129, v129
	v_exp_f32_e32 v130, v130
	v_exp_f32_e32 v131, v131
	v_add_f32_e32 v128, 1.0, v128
	v_add_f32_e32 v129, 1.0, v129
	v_add_f32_e32 v130, 1.0, v130
	v_add_f32_e32 v131, 1.0, v131
	v_rcp_f32_e32 v128, v128
	v_rcp_f32_e32 v129, v129
	v_rcp_f32_e32 v130, v130
	v_rcp_f32_e32 v131, v131
	v_pk_fma_f32 v[140:141], v[128:129], v[156:157], v[140:141]
	s_nop 0
	v_pk_fma_f32 v[142:143], v[130:131], v[158:159], v[142:143]
	global_store_dwordx4 v[164:165], v[140:143], off offset:512
	v_mul_f32_e32 v128, 0xbfb8aa3b, v80
	v_mul_f32_e32 v129, 0xbfb8aa3b, v81
	v_mul_f32_e32 v130, 0xbfb8aa3b, v82
	v_mul_f32_e32 v131, 0xbfb8aa3b, v83
	v_exp_f32_e32 v128, v128
	v_exp_f32_e32 v129, v129
	v_exp_f32_e32 v130, v130
	v_exp_f32_e32 v131, v131
	v_add_f32_e32 v128, 1.0, v128
	v_add_f32_e32 v129, 1.0, v129
	v_add_f32_e32 v130, 1.0, v130
	v_add_f32_e32 v131, 1.0, v131
	v_rcp_f32_e32 v128, v128
	v_rcp_f32_e32 v129, v129
	v_rcp_f32_e32 v130, v130
	v_rcp_f32_e32 v131, v131
	v_pk_fma_f32 v[144:145], v[128:129], v[160:161], v[144:145]
	s_nop 0
	v_pk_fma_f32 v[146:147], v[130:131], v[162:163], v[146:147]
	global_store_dwordx4 v[164:165], v[144:147], off offset:576
	s_nop 1
	v_add_u32_e32 v250, s54, v197
	v_ashrrev_i32_e32 v251, 31, v250
	v_lshlrev_b64 v[250:251], 13, v[250:251]
	v_lshl_add_u64 v[250:251], v[250:251], 0, v[190:191]
	v_lshl_add_u64 v[164:165], v[250:251], 0, s[4:5]
	v_lshl_add_u64 v[166:167], v[250:251], 0, s[30:31]
	global_load_dwordx4 v[132:135], v[164:165], off
	global_load_dwordx4 v[136:139], v[164:165], off offset:64
	global_load_dwordx4 v[140:143], v[164:165], off offset:512
	global_load_dwordx4 v[144:147], v[164:165], off offset:576
	global_load_dwordx4 v[148:151], v[166:167], off
	global_load_dwordx4 v[152:155], v[166:167], off offset:64
	global_load_dwordx4 v[156:159], v[166:167], off offset:512
	global_load_dwordx4 v[160:163], v[166:167], off offset:576
	s_waitcnt vmcnt(12)
	v_mul_f32_e32 v128, 0xbfb8aa3b, v76
	v_mul_f32_e32 v129, 0xbfb8aa3b, v77
	v_mul_f32_e32 v130, 0xbfb8aa3b, v78
	v_mul_f32_e32 v131, 0xbfb8aa3b, v79
	v_exp_f32_e32 v128, v128
	v_exp_f32_e32 v129, v129
	v_exp_f32_e32 v130, v130
	v_exp_f32_e32 v131, v131
	v_add_f32_e32 v128, 1.0, v128
	v_add_f32_e32 v129, 1.0, v129
	v_add_f32_e32 v130, 1.0, v130
	v_add_f32_e32 v131, 1.0, v131
	v_rcp_f32_e32 v128, v128
	v_rcp_f32_e32 v129, v129
	v_rcp_f32_e32 v130, v130
	v_rcp_f32_e32 v131, v131
	v_pk_fma_f32 v[204:205], v[128:129], v[220:221], v[204:205]
	s_nop 0
	v_pk_fma_f32 v[206:207], v[130:131], v[222:223], v[206:207]
	global_store_dwordx4 v[224:225], v[204:207], off
	v_mul_f32_e32 v128, 0xbfb8aa3b, v72
	v_mul_f32_e32 v129, 0xbfb8aa3b, v73
	v_mul_f32_e32 v130, 0xbfb8aa3b, v74
	v_mul_f32_e32 v131, 0xbfb8aa3b, v75
	v_exp_f32_e32 v128, v128
	v_exp_f32_e32 v129, v129
	v_exp_f32_e32 v130, v130
	v_exp_f32_e32 v131, v131
	v_add_f32_e32 v128, 1.0, v128
	v_add_f32_e32 v129, 1.0, v129
	v_add_f32_e32 v130, 1.0, v130
	v_add_f32_e32 v131, 1.0, v131
	v_rcp_f32_e32 v128, v128
	v_rcp_f32_e32 v129, v129
	v_rcp_f32_e32 v130, v130
	v_rcp_f32_e32 v131, v131
	v_pk_fma_f32 v[208:209], v[128:129], v[232:233], v[208:209]
	s_nop 0
	v_pk_fma_f32 v[210:211], v[130:131], v[234:235], v[210:211]
	global_store_dwordx4 v[224:225], v[208:211], off offset:64
	v_mul_f32_e32 v128, 0xbfb8aa3b, v68
	v_mul_f32_e32 v129, 0xbfb8aa3b, v69
	v_mul_f32_e32 v130, 0xbfb8aa3b, v70
	v_mul_f32_e32 v131, 0xbfb8aa3b, v71
	v_exp_f32_e32 v128, v128
	v_exp_f32_e32 v129, v129
	v_exp_f32_e32 v130, v130
	v_exp_f32_e32 v131, v131
	v_add_f32_e32 v128, 1.0, v128
	v_add_f32_e32 v129, 1.0, v129
	v_add_f32_e32 v130, 1.0, v130
	v_add_f32_e32 v131, 1.0, v131
	v_rcp_f32_e32 v128, v128
	v_rcp_f32_e32 v129, v129
	v_rcp_f32_e32 v130, v130
	v_rcp_f32_e32 v131, v131
	v_pk_fma_f32 v[212:213], v[128:129], v[240:241], v[212:213]
	s_nop 0
	v_pk_fma_f32 v[214:215], v[130:131], v[242:243], v[214:215]
	global_store_dwordx4 v[224:225], v[212:215], off offset:512
	v_mul_f32_e32 v128, 0xbfb8aa3b, v64
	v_mul_f32_e32 v129, 0xbfb8aa3b, v65
	v_mul_f32_e32 v130, 0xbfb8aa3b, v66
	v_mul_f32_e32 v131, 0xbfb8aa3b, v67
	v_exp_f32_e32 v128, v128
	v_exp_f32_e32 v129, v129
	v_exp_f32_e32 v130, v130
	v_exp_f32_e32 v131, v131
	v_add_f32_e32 v128, 1.0, v128
	v_add_f32_e32 v129, 1.0, v129
	v_add_f32_e32 v130, 1.0, v130
	v_add_f32_e32 v131, 1.0, v131
	v_rcp_f32_e32 v128, v128
	v_rcp_f32_e32 v129, v129
	v_rcp_f32_e32 v130, v130
	v_rcp_f32_e32 v131, v131
	v_pk_fma_f32 v[216:217], v[128:129], v[244:245], v[216:217]
	s_nop 0
	v_pk_fma_f32 v[218:219], v[130:131], v[246:247], v[218:219]
	global_store_dwordx4 v[224:225], v[216:219], off offset:576
	s_nop 1
	v_add_u32_e32 v250, s54, v198
	v_ashrrev_i32_e32 v251, 31, v250
	v_lshlrev_b64 v[250:251], 13, v[250:251]
	v_lshl_add_u64 v[250:251], v[250:251], 0, v[190:191]
	v_lshl_add_u64 v[224:225], v[250:251], 0, s[4:5]
	v_lshl_add_u64 v[248:249], v[250:251], 0, s[30:31]
	global_load_dwordx4 v[204:207], v[224:225], off
	global_load_dwordx4 v[208:211], v[224:225], off offset:64
	global_load_dwordx4 v[212:215], v[224:225], off offset:512
	global_load_dwordx4 v[216:219], v[224:225], off offset:576
	global_load_dwordx4 v[220:223], v[248:249], off
	global_load_dwordx4 v[232:235], v[248:249], off offset:64
	global_load_dwordx4 v[240:243], v[248:249], off offset:512
	global_load_dwordx4 v[244:247], v[248:249], off offset:576
	s_waitcnt vmcnt(12)
	v_mul_f32_e32 v128, 0xbfb8aa3b, v60
	v_mul_f32_e32 v129, 0xbfb8aa3b, v61
	v_mul_f32_e32 v130, 0xbfb8aa3b, v62
	v_mul_f32_e32 v131, 0xbfb8aa3b, v63
	v_exp_f32_e32 v128, v128
	v_exp_f32_e32 v129, v129
	v_exp_f32_e32 v130, v130
	v_exp_f32_e32 v131, v131
	v_add_f32_e32 v128, 1.0, v128
	v_add_f32_e32 v129, 1.0, v129
	v_add_f32_e32 v130, 1.0, v130
	v_add_f32_e32 v131, 1.0, v131
	v_rcp_f32_e32 v128, v128
	v_rcp_f32_e32 v129, v129
	v_rcp_f32_e32 v130, v130
	v_rcp_f32_e32 v131, v131
	v_pk_fma_f32 v[132:133], v[128:129], v[148:149], v[132:133]
	s_nop 0
	v_pk_fma_f32 v[134:135], v[130:131], v[150:151], v[134:135]
	global_store_dwordx4 v[164:165], v[132:135], off
	v_mul_f32_e32 v128, 0xbfb8aa3b, v56
	v_mul_f32_e32 v129, 0xbfb8aa3b, v57
	v_mul_f32_e32 v130, 0xbfb8aa3b, v58
	v_mul_f32_e32 v131, 0xbfb8aa3b, v59
	v_exp_f32_e32 v128, v128
	v_exp_f32_e32 v129, v129
	v_exp_f32_e32 v130, v130
	v_exp_f32_e32 v131, v131
	v_add_f32_e32 v128, 1.0, v128
	v_add_f32_e32 v129, 1.0, v129
	v_add_f32_e32 v130, 1.0, v130
	v_add_f32_e32 v131, 1.0, v131
	v_rcp_f32_e32 v128, v128
	v_rcp_f32_e32 v129, v129
	v_rcp_f32_e32 v130, v130
	v_rcp_f32_e32 v131, v131
	v_pk_fma_f32 v[136:137], v[128:129], v[152:153], v[136:137]
	s_nop 0
	v_pk_fma_f32 v[138:139], v[130:131], v[154:155], v[138:139]
	global_store_dwordx4 v[164:165], v[136:139], off offset:64
	v_mul_f32_e32 v128, 0xbfb8aa3b, v52
	v_mul_f32_e32 v129, 0xbfb8aa3b, v53
	v_mul_f32_e32 v130, 0xbfb8aa3b, v54
	v_mul_f32_e32 v131, 0xbfb8aa3b, v55
	v_exp_f32_e32 v128, v128
	v_exp_f32_e32 v129, v129
	v_exp_f32_e32 v130, v130
	v_exp_f32_e32 v131, v131
	v_add_f32_e32 v128, 1.0, v128
	v_add_f32_e32 v129, 1.0, v129
	v_add_f32_e32 v130, 1.0, v130
	v_add_f32_e32 v131, 1.0, v131
	v_rcp_f32_e32 v128, v128
	v_rcp_f32_e32 v129, v129
	v_rcp_f32_e32 v130, v130
	v_rcp_f32_e32 v131, v131
	v_pk_fma_f32 v[140:141], v[128:129], v[156:157], v[140:141]
	s_nop 0
	v_pk_fma_f32 v[142:143], v[130:131], v[158:159], v[142:143]
	global_store_dwordx4 v[164:165], v[140:143], off offset:512
	v_mul_f32_e32 v128, 0xbfb8aa3b, v48
	v_mul_f32_e32 v129, 0xbfb8aa3b, v49
	v_mul_f32_e32 v130, 0xbfb8aa3b, v50
	v_mul_f32_e32 v131, 0xbfb8aa3b, v51
	v_exp_f32_e32 v128, v128
	v_exp_f32_e32 v129, v129
	v_exp_f32_e32 v130, v130
	v_exp_f32_e32 v131, v131
	v_add_f32_e32 v128, 1.0, v128
	v_add_f32_e32 v129, 1.0, v129
	v_add_f32_e32 v130, 1.0, v130
	v_add_f32_e32 v131, 1.0, v131
	v_rcp_f32_e32 v128, v128
	v_rcp_f32_e32 v129, v129
	v_rcp_f32_e32 v130, v130
	v_rcp_f32_e32 v131, v131
	v_pk_fma_f32 v[144:145], v[128:129], v[160:161], v[144:145]
	s_nop 0
	v_pk_fma_f32 v[146:147], v[130:131], v[162:163], v[146:147]
	global_store_dwordx4 v[164:165], v[144:147], off offset:576
	s_nop 1
	v_add_u32_e32 v250, s54, v199
	v_ashrrev_i32_e32 v251, 31, v250
	v_lshlrev_b64 v[250:251], 13, v[250:251]
	v_lshl_add_u64 v[250:251], v[250:251], 0, v[190:191]
	v_lshl_add_u64 v[164:165], v[250:251], 0, s[4:5]
	v_lshl_add_u64 v[166:167], v[250:251], 0, s[30:31]
	global_load_dwordx4 v[132:135], v[164:165], off
	global_load_dwordx4 v[136:139], v[164:165], off offset:64
	global_load_dwordx4 v[140:143], v[164:165], off offset:512
	global_load_dwordx4 v[144:147], v[164:165], off offset:576
	global_load_dwordx4 v[148:151], v[166:167], off
	global_load_dwordx4 v[152:155], v[166:167], off offset:64
	global_load_dwordx4 v[156:159], v[166:167], off offset:512
	global_load_dwordx4 v[160:163], v[166:167], off offset:576
	s_waitcnt vmcnt(12)
	v_mul_f32_e32 v128, 0xbfb8aa3b, v44
	v_mul_f32_e32 v129, 0xbfb8aa3b, v45
	v_mul_f32_e32 v130, 0xbfb8aa3b, v46
	v_mul_f32_e32 v131, 0xbfb8aa3b, v47
	v_exp_f32_e32 v128, v128
	v_exp_f32_e32 v129, v129
	v_exp_f32_e32 v130, v130
	v_exp_f32_e32 v131, v131
	v_add_f32_e32 v128, 1.0, v128
	v_add_f32_e32 v129, 1.0, v129
	v_add_f32_e32 v130, 1.0, v130
	v_add_f32_e32 v131, 1.0, v131
	v_rcp_f32_e32 v128, v128
	v_rcp_f32_e32 v129, v129
	v_rcp_f32_e32 v130, v130
	v_rcp_f32_e32 v131, v131
	v_pk_fma_f32 v[204:205], v[128:129], v[220:221], v[204:205]
	s_nop 0
	v_pk_fma_f32 v[206:207], v[130:131], v[222:223], v[206:207]
	global_store_dwordx4 v[224:225], v[204:207], off
	v_mul_f32_e32 v128, 0xbfb8aa3b, v40
	v_mul_f32_e32 v129, 0xbfb8aa3b, v41
	v_mul_f32_e32 v130, 0xbfb8aa3b, v42
	v_mul_f32_e32 v131, 0xbfb8aa3b, v43
	v_exp_f32_e32 v128, v128
	v_exp_f32_e32 v129, v129
	v_exp_f32_e32 v130, v130
	v_exp_f32_e32 v131, v131
	v_add_f32_e32 v128, 1.0, v128
	v_add_f32_e32 v129, 1.0, v129
	v_add_f32_e32 v130, 1.0, v130
	v_add_f32_e32 v131, 1.0, v131
	v_rcp_f32_e32 v128, v128
	v_rcp_f32_e32 v129, v129
	v_rcp_f32_e32 v130, v130
	v_rcp_f32_e32 v131, v131
	v_pk_fma_f32 v[208:209], v[128:129], v[232:233], v[208:209]
	s_nop 0
	v_pk_fma_f32 v[210:211], v[130:131], v[234:235], v[210:211]
	global_store_dwordx4 v[224:225], v[208:211], off offset:64
	v_mul_f32_e32 v128, 0xbfb8aa3b, v36
	v_mul_f32_e32 v129, 0xbfb8aa3b, v37
	v_mul_f32_e32 v130, 0xbfb8aa3b, v38
	v_mul_f32_e32 v131, 0xbfb8aa3b, v39
	v_exp_f32_e32 v128, v128
	v_exp_f32_e32 v129, v129
	v_exp_f32_e32 v130, v130
	v_exp_f32_e32 v131, v131
	v_add_f32_e32 v128, 1.0, v128
	v_add_f32_e32 v129, 1.0, v129
	v_add_f32_e32 v130, 1.0, v130
	v_add_f32_e32 v131, 1.0, v131
	v_rcp_f32_e32 v128, v128
	v_rcp_f32_e32 v129, v129
	v_rcp_f32_e32 v130, v130
	v_rcp_f32_e32 v131, v131
	v_pk_fma_f32 v[212:213], v[128:129], v[240:241], v[212:213]
	s_nop 0
	v_pk_fma_f32 v[214:215], v[130:131], v[242:243], v[214:215]
	global_store_dwordx4 v[224:225], v[212:215], off offset:512
	v_mul_f32_e32 v128, 0xbfb8aa3b, v32
	v_mul_f32_e32 v129, 0xbfb8aa3b, v33
	v_mul_f32_e32 v130, 0xbfb8aa3b, v34
	v_mul_f32_e32 v131, 0xbfb8aa3b, v35
	v_exp_f32_e32 v128, v128
	v_exp_f32_e32 v129, v129
	v_exp_f32_e32 v130, v130
	v_exp_f32_e32 v131, v131
	v_add_f32_e32 v128, 1.0, v128
	v_add_f32_e32 v129, 1.0, v129
	v_add_f32_e32 v130, 1.0, v130
	v_add_f32_e32 v131, 1.0, v131
	v_rcp_f32_e32 v128, v128
	v_rcp_f32_e32 v129, v129
	v_rcp_f32_e32 v130, v130
	v_rcp_f32_e32 v131, v131
	v_pk_fma_f32 v[216:217], v[128:129], v[244:245], v[216:217]
	s_nop 0
	v_pk_fma_f32 v[218:219], v[130:131], v[246:247], v[218:219]
	global_store_dwordx4 v[224:225], v[216:219], off offset:576
	s_nop 1
	v_add_u32_e32 v250, s54, v200
	v_ashrrev_i32_e32 v251, 31, v250
	v_lshlrev_b64 v[250:251], 13, v[250:251]
	v_lshl_add_u64 v[250:251], v[250:251], 0, v[190:191]
	v_lshl_add_u64 v[224:225], v[250:251], 0, s[4:5]
	v_lshl_add_u64 v[248:249], v[250:251], 0, s[30:31]
	global_load_dwordx4 v[204:207], v[224:225], off
	global_load_dwordx4 v[208:211], v[224:225], off offset:64
	global_load_dwordx4 v[212:215], v[224:225], off offset:512
	global_load_dwordx4 v[216:219], v[224:225], off offset:576
	global_load_dwordx4 v[220:223], v[248:249], off
	global_load_dwordx4 v[232:235], v[248:249], off offset:64
	global_load_dwordx4 v[240:243], v[248:249], off offset:512
	global_load_dwordx4 v[244:247], v[248:249], off offset:576
	s_waitcnt vmcnt(12)
	v_mul_f32_e32 v128, 0xbfb8aa3b, v28
	v_mul_f32_e32 v129, 0xbfb8aa3b, v29
	v_mul_f32_e32 v130, 0xbfb8aa3b, v30
	v_mul_f32_e32 v131, 0xbfb8aa3b, v31
	v_exp_f32_e32 v128, v128
	v_exp_f32_e32 v129, v129
	v_exp_f32_e32 v130, v130
	v_exp_f32_e32 v131, v131
	v_add_f32_e32 v128, 1.0, v128
	v_add_f32_e32 v129, 1.0, v129
	v_add_f32_e32 v130, 1.0, v130
	v_add_f32_e32 v131, 1.0, v131
	v_rcp_f32_e32 v128, v128
	v_rcp_f32_e32 v129, v129
	v_rcp_f32_e32 v130, v130
	v_rcp_f32_e32 v131, v131
	v_pk_fma_f32 v[132:133], v[128:129], v[148:149], v[132:133]
	s_nop 0
	v_pk_fma_f32 v[134:135], v[130:131], v[150:151], v[134:135]
	global_store_dwordx4 v[164:165], v[132:135], off
	v_mul_f32_e32 v128, 0xbfb8aa3b, v24
	v_mul_f32_e32 v129, 0xbfb8aa3b, v25
	v_mul_f32_e32 v130, 0xbfb8aa3b, v26
	v_mul_f32_e32 v131, 0xbfb8aa3b, v27
	v_exp_f32_e32 v128, v128
	v_exp_f32_e32 v129, v129
	v_exp_f32_e32 v130, v130
	v_exp_f32_e32 v131, v131
	v_add_f32_e32 v128, 1.0, v128
	v_add_f32_e32 v129, 1.0, v129
	v_add_f32_e32 v130, 1.0, v130
	v_add_f32_e32 v131, 1.0, v131
	v_rcp_f32_e32 v128, v128
	v_rcp_f32_e32 v129, v129
	v_rcp_f32_e32 v130, v130
	v_rcp_f32_e32 v131, v131
	v_pk_fma_f32 v[136:137], v[128:129], v[152:153], v[136:137]
	s_nop 0
	v_pk_fma_f32 v[138:139], v[130:131], v[154:155], v[138:139]
	global_store_dwordx4 v[164:165], v[136:139], off offset:64
	v_mul_f32_e32 v128, 0xbfb8aa3b, v20
	v_mul_f32_e32 v129, 0xbfb8aa3b, v21
	v_mul_f32_e32 v130, 0xbfb8aa3b, v22
	v_mul_f32_e32 v131, 0xbfb8aa3b, v23
	v_exp_f32_e32 v128, v128
	v_exp_f32_e32 v129, v129
	v_exp_f32_e32 v130, v130
	v_exp_f32_e32 v131, v131
	v_add_f32_e32 v128, 1.0, v128
	v_add_f32_e32 v129, 1.0, v129
	v_add_f32_e32 v130, 1.0, v130
	v_add_f32_e32 v131, 1.0, v131
	v_rcp_f32_e32 v128, v128
	v_rcp_f32_e32 v129, v129
	v_rcp_f32_e32 v130, v130
	v_rcp_f32_e32 v131, v131
	v_pk_fma_f32 v[140:141], v[128:129], v[156:157], v[140:141]
	s_nop 0
	v_pk_fma_f32 v[142:143], v[130:131], v[158:159], v[142:143]
	global_store_dwordx4 v[164:165], v[140:143], off offset:512
	v_mul_f32_e32 v128, 0xbfb8aa3b, v16
	v_mul_f32_e32 v129, 0xbfb8aa3b, v17
	v_mul_f32_e32 v130, 0xbfb8aa3b, v18
	v_mul_f32_e32 v131, 0xbfb8aa3b, v19
	v_exp_f32_e32 v128, v128
	v_exp_f32_e32 v129, v129
	v_exp_f32_e32 v130, v130
	v_exp_f32_e32 v131, v131
	v_add_f32_e32 v128, 1.0, v128
	v_add_f32_e32 v129, 1.0, v129
	v_add_f32_e32 v130, 1.0, v130
	v_add_f32_e32 v131, 1.0, v131
	v_rcp_f32_e32 v128, v128
	v_rcp_f32_e32 v129, v129
	v_rcp_f32_e32 v130, v130
	v_rcp_f32_e32 v131, v131
	v_pk_fma_f32 v[144:145], v[128:129], v[160:161], v[144:145]
	s_nop 0
	v_pk_fma_f32 v[146:147], v[130:131], v[162:163], v[146:147]
	global_store_dwordx4 v[164:165], v[144:147], off offset:576
	s_waitcnt vmcnt(4)
	v_mul_f32_e32 v128, 0xbfb8aa3b, v12
	v_mul_f32_e32 v129, 0xbfb8aa3b, v13
	v_mul_f32_e32 v130, 0xbfb8aa3b, v14
	v_mul_f32_e32 v131, 0xbfb8aa3b, v15
	v_exp_f32_e32 v128, v128
	v_exp_f32_e32 v129, v129
	v_exp_f32_e32 v130, v130
	v_exp_f32_e32 v131, v131
	v_add_f32_e32 v128, 1.0, v128
	v_add_f32_e32 v129, 1.0, v129
	v_add_f32_e32 v130, 1.0, v130
	v_add_f32_e32 v131, 1.0, v131
	v_rcp_f32_e32 v128, v128
	v_rcp_f32_e32 v129, v129
	v_rcp_f32_e32 v130, v130
	v_rcp_f32_e32 v131, v131
	v_pk_fma_f32 v[204:205], v[128:129], v[220:221], v[204:205]
	s_nop 0
	v_pk_fma_f32 v[206:207], v[130:131], v[222:223], v[206:207]
	global_store_dwordx4 v[224:225], v[204:207], off
	v_mul_f32_e32 v128, 0xbfb8aa3b, v8
	v_mul_f32_e32 v129, 0xbfb8aa3b, v9
	v_mul_f32_e32 v130, 0xbfb8aa3b, v10
	v_mul_f32_e32 v131, 0xbfb8aa3b, v11
	v_exp_f32_e32 v128, v128
	v_exp_f32_e32 v129, v129
	v_exp_f32_e32 v130, v130
	v_exp_f32_e32 v131, v131
	v_add_f32_e32 v128, 1.0, v128
	v_add_f32_e32 v129, 1.0, v129
	v_add_f32_e32 v130, 1.0, v130
	v_add_f32_e32 v131, 1.0, v131
	v_rcp_f32_e32 v128, v128
	v_rcp_f32_e32 v129, v129
	v_rcp_f32_e32 v130, v130
	v_rcp_f32_e32 v131, v131
	v_pk_fma_f32 v[208:209], v[128:129], v[232:233], v[208:209]
	s_nop 0
	v_pk_fma_f32 v[210:211], v[130:131], v[234:235], v[210:211]
	global_store_dwordx4 v[224:225], v[208:211], off offset:64
	v_mul_f32_e32 v128, 0xbfb8aa3b, v4
	v_mul_f32_e32 v129, 0xbfb8aa3b, v5
	v_mul_f32_e32 v130, 0xbfb8aa3b, v6
	v_mul_f32_e32 v131, 0xbfb8aa3b, v7
	v_exp_f32_e32 v128, v128
	v_exp_f32_e32 v129, v129
	v_exp_f32_e32 v130, v130
	v_exp_f32_e32 v131, v131
	v_add_f32_e32 v128, 1.0, v128
	v_add_f32_e32 v129, 1.0, v129
	v_add_f32_e32 v130, 1.0, v130
	v_add_f32_e32 v131, 1.0, v131
	v_rcp_f32_e32 v128, v128
	v_rcp_f32_e32 v129, v129
	v_rcp_f32_e32 v130, v130
	v_rcp_f32_e32 v131, v131
	v_pk_fma_f32 v[212:213], v[128:129], v[240:241], v[212:213]
	s_nop 0
	v_pk_fma_f32 v[214:215], v[130:131], v[242:243], v[214:215]
	global_store_dwordx4 v[224:225], v[212:215], off offset:512
	v_mul_f32_e32 v128, 0xbfb8aa3b, v0
	v_mul_f32_e32 v129, 0xbfb8aa3b, v1
	v_mul_f32_e32 v130, 0xbfb8aa3b, v2
	v_mul_f32_e32 v131, 0xbfb8aa3b, v3
	v_exp_f32_e32 v128, v128
	v_exp_f32_e32 v129, v129
	v_exp_f32_e32 v130, v130
	v_exp_f32_e32 v131, v131
	v_add_f32_e32 v128, 1.0, v128
	v_add_f32_e32 v129, 1.0, v129
	v_add_f32_e32 v130, 1.0, v130
	v_add_f32_e32 v131, 1.0, v131
	v_rcp_f32_e32 v128, v128
	v_rcp_f32_e32 v129, v129
	v_rcp_f32_e32 v130, v130
	v_rcp_f32_e32 v131, v131
	v_pk_fma_f32 v[216:217], v[128:129], v[244:245], v[216:217]
	s_nop 0
	v_pk_fma_f32 v[218:219], v[130:131], v[246:247], v[218:219]
	global_store_dwordx4 v[224:225], v[216:219], off offset:576
